# G4 last layer: the 128 workgroups with one unit fewer start half a unit late so the epilogue store bursts of the two groups interleave (on top of E1+E3)
# speedup vs baseline: 1.0057x; 1.0007x over previous
.LBB0_1142:
	s_or_b64 exec, exec, s[0:1]
	v_readlane_b32 s4, v252, 4
	s_mov_b64 s[0:1], 0
	v_readlane_b32 s18, v252, 18
	s_waitcnt lgkmcnt(0)
	s_barrier
	v_readlane_b32 s19, v252, 19
	s_add_u32 s58, s18, s0
	s_addc_u32 s59, s19, s1
	s_add_u32 s56, s58, 0x6a00000
	v_mov_b32_e32 v1, v0
	v_readlane_b32 s33, v252, 0
	v_readlane_b32 s61, v252, 3
	s_addc_u32 s57, s59, 0
	s_cmpk_eq_i32 s61, 0x100
	s_cselect_b64 s[2:3], -1, 0
	s_cmpk_lg_i32 s61, 0x100
	v_mov_b32_e32 v10, v0
	v_readfirstlane_b32 s60, v1
	s_cselect_b64 s[22:23], -1, 0
	s_cmpk_lt_i32 s33, 0x80
	s_cbranch_scc1 .Lg4_nodelay
	v_readlane_b32 s24, v254, 46
	s_nop 0
	s_cmp_lg_u32 s24, 0
	s_cbranch_scc1 .Lg4_nodelay
	s_movk_i32 s24, 12
.Lg4_dl:
	s_sleep 127
	s_add_i32 s24, s24, -1
	s_cmp_lg_u32 s24, 0
	s_cbranch_scc1 .Lg4_dl
.Lg4_nodelay:
	s_and_b64 vcc, exec, s[2:3]
	v_readfirstlane_b32 s4, v10
	v_readlane_b32 s5, v252, 5
	v_readlane_b32 s6, v252, 6
	v_readlane_b32 s7, v252, 7
	v_readlane_b32 s8, v252, 8
	v_readlane_b32 s9, v252, 9
	v_readlane_b32 s10, v252, 10
	v_readlane_b32 s11, v252, 11
	v_readlane_b32 s12, v252, 12
	v_readlane_b32 s13, v252, 13
	v_readlane_b32 s14, v252, 14
	v_readlane_b32 s15, v252, 15
	v_readlane_b32 s16, v252, 16
	v_readlane_b32 s17, v252, 17
	s_cbranch_vccnz .LBB0_1145
	s_mov_b64 s[24:25], 0
	s_cmpk_lt_i32 s33, 0x1080
	s_mov_b64 s[26:27], 0
	s_cbranch_scc0 .LBB0_1146
	s_ashr_i32 s0, s33, 31
	s_lshr_b32 s0, s0, 29
	s_add_i32 s0, s33, s0
	s_ashr_i32 s1, s0, 3
	s_and_b32 s0, s0, -8
	s_sub_i32 s0, s33, s0
	s_cmp_lt_i32 s0, 0
	s_movk_i32 s5, 0x211
	s_cselect_b32 s5, s5, 0x210
	s_mul_i32 s0, s0, s5
	s_add_i32 s0, s0, s1
	s_ashr_i32 s1, s0, 31
	s_lshr_b32 s1, s1, 23
	s_add_i32 s1, s0, s1
	s_ashr_i32 s5, s1, 9
	s_lshl_b32 s5, s5, 3
	s_sub_i32 s6, 0x42, s5
	s_min_u32 s6, s6, 8
	s_and_b32 s1, s1, 0xfffffe00
	s_sub_i32 s7, s0, s1
	v_cvt_f32_ubyte0_e32 v3, s6
	v_cvt_f32_i32_e32 v2, s7
	v_rcp_iflag_f32_e32 v4, v3
	s_ashr_i32 s0, s7, 30
	s_or_b32 s8, s0, 1
	s_mov_b64 s[26:27], -1
	v_mul_f32_e32 v4, v2, v4
	v_trunc_f32_e32 v4, v4
	v_fma_f32 v2, -v4, v3, v2
	v_cvt_i32_f32_e32 v4, v4
	v_cmp_ge_f32_e64 s[0:1], |v2|, v3
	s_and_b64 s[0:1], s[0:1], exec
	s_cselect_b32 s0, s8, 0
	v_readfirstlane_b32 s1, v4
	s_add_i32 s0, s1, s0
	s_sext_i32_i16 s48, s0
	s_mul_i32 s0, s0, s6
	s_sub_i32 s0, s7, s0
	s_sext_i32_i16 s0, s0
	s_add_i32 s0, s5, s0
	s_branch .LBB0_1146
